# P10|P11 seam XCD-local when the placement census finds each XCC holding one bx%8 class (skips L2 writeback + cross-XCC rendezvous); else unchanged barrier
# baseline (speedup 1.0000x reference)
; #define LAS __attribute__((address_space(3)))
; __global__ void __launch_bounds__(512, 2) fwd_mega(Args args) {
;     extern __shared__ __attribute__((aligned(16))) unsigned char lds_raw[];
;     LAS unsigned char* lds = (LAS unsigned char*)lds_raw;
;     cg::grid_group grid = cg::this_grid();
;     const int tid = threadIdx.x, lane = tid & 63, wave = __builtin_amdgcn_readfirstlane(tid >> 6);
;     const int G = gridDim.x, bx = blockIdx.x;
;     const float* x = args.in[0]; const float* mem = args.in[1]; const int* positions = (const int*)args.in[2];
;     float* out = args.out;
;     const int lo = args.ph_lo, hi = args.ph_hi;
;     ...
;     if (args.ph_lo < 0) grid.sync();
_Z8fwd_mega4Args:
	s_mov_b32 s98, 0
	s_mov_b32 s96, s2
	s_load_dwordx4 s[84:87], s[0:1], 0x100
	s_load_dword s2, s[0:1], 0x110
	s_add_u32 s4, s0, 0x108
	s_addc_u32 s5, s1, 0
	v_and_b32_e32 v196, 0x3ff, v0
	s_waitcnt lgkmcnt(0)
	s_cmp_gt_i32 s84, -1
	v_writelane_b32 v249, s2, 0
	s_movk_i32 s2, 0x3ff
	v_readfirstlane_b32 s10, v196
	s_cbranch_scc1 .LBB0_12
	v_lshrrev_b32_e32 v1, 20, v0
	v_lshrrev_b32_e32 v0, 10, v0
	v_or_b32_e32 v0, v0, v1
	v_and_or_b32 v0, v0, s2, v196
	v_cmp_eq_u32_e32 vcc, 0, v0
	s_barrier
	s_and_saveexec_b64 s[2:3], vcc
	s_cbranch_execz .LBB0_11
	buffer_wbl2 sc1
	s_load_dwordx2 s[4:5], s[4:5], 0x58
	s_mov_b64 s[6:7], exec
	v_mbcnt_lo_u32_b32 v0, s6, 0
	v_mbcnt_hi_u32_b32 v0, s7, v0
	v_cmp_eq_u32_e32 vcc, 0, v0
	s_waitcnt lgkmcnt(0)
	s_load_dword s11, s[4:5], 0x28
	s_and_saveexec_b64 s[8:9], vcc
	s_cbranch_execz .LBB0_4
	s_bcnt1_i32_b64 s6, s[6:7]
	v_mov_b32_e32 v1, 0
	v_mov_b32_e32 v2, s6
	global_atomic_add v1, v1, v2, s[4:5] offset:32 sc0

; #define LAS __attribute__((address_space(3)))
; __device__ __forceinline__ unsigned xb_add(unsigned* p, unsigned v) { return __hip_atomic_fetch_add(p, v, __ATOMIC_RELAXED, __HIP_MEMORY_SCOPE_AGENT); }
; __device__ __forceinline__ unsigned xb_xcc_id() { return (unsigned)__builtin_amdgcn_s_getreg((3 << 11) | 20) & 0xFu; }
; __device__ __forceinline__ XcdBarrier xcd_barrier_post(unsigned* bar, volatile LAS unsigned* st) {
;     XcdBarrier b; b.bar = bar; b.x = xb_xcc_id(); b.st = st;
;     if (threadIdx.x == 0) (void)xb_add(&bar[XB_XCNT(b.x)], 1u);
;     return b;
; }
; __global__ void __launch_bounds__(512, 2) fwd_mega(Args args) {
;     ...
;     if (tid < 4) ((LAS unsigned*)(lds + 131072 + 1024))[tid] = 0u;
;     __syncthreads();
;     XcdBarrier xbar = xcd_barrier_post((unsigned*)(args.ws + S_BAR), (volatile LAS unsigned*)(lds + 131072 + 1024));
.LBB0_12:
	s_load_dwordx16 s[12:27], s[0:1], 0xc0
	v_cmp_gt_u32_e32 vcc, 4, v196
	s_waitcnt lgkmcnt(0)
	v_writelane_b32 v249, s12, 1
	s_nop 1
	v_writelane_b32 v249, s13, 2
	v_writelane_b32 v249, s14, 3
	v_writelane_b32 v249, s15, 4
	v_writelane_b32 v249, s16, 5
	v_writelane_b32 v249, s17, 6
	v_writelane_b32 v249, s18, 7
	v_writelane_b32 v249, s19, 8
	v_writelane_b32 v249, s20, 9
	v_writelane_b32 v249, s21, 10
	v_writelane_b32 v249, s22, 11
	v_writelane_b32 v249, s23, 12
	v_writelane_b32 v249, s24, 13
	v_writelane_b32 v249, s25, 14
	v_writelane_b32 v249, s26, 15
	v_writelane_b32 v249, s27, 16
	s_and_saveexec_b64 s[2:3], vcc
	v_lshl_add_u32 v0, v196, 2, 0
	v_add_u32_e32 v0, 0x20400, v0
	v_mov_b32_e32 v1, 0
	ds_write_b32 v0, v1
	s_or_b64 exec, exec, s[2:3]
	s_load_dwordx16 s[36:51], s[0:1], 0x0
	s_load_dwordx16 s[52:67], s[0:1], 0x80
	s_waitcnt lgkmcnt(0)
	s_barrier
	v_writelane_b32 v249, s36, 17
	v_cmp_eq_u32_e64 s[2:3], 0, v196
	s_nop 0
	v_writelane_b32 v249, s37, 18
	v_writelane_b32 v249, s38, 19
	v_writelane_b32 v249, s39, 20
	v_writelane_b32 v249, s40, 21
	v_writelane_b32 v249, s41, 22
	v_writelane_b32 v249, s42, 23
	v_writelane_b32 v249, s43, 24
	v_writelane_b32 v249, s44, 25
	v_writelane_b32 v249, s45, 26
	v_writelane_b32 v249, s46, 27
	v_writelane_b32 v249, s47, 28
	v_writelane_b32 v249, s48, 29
	v_writelane_b32 v249, s49, 30
	v_writelane_b32 v249, s50, 31
	v_writelane_b32 v249, s51, 32
	s_load_dwordx16 s[36:51], s[0:1], 0x40
	s_waitcnt lgkmcnt(0)
	v_writelane_b32 v249, s36, 33
	s_nop 1
	v_writelane_b32 v249, s37, 34
	v_writelane_b32 v249, s38, 35
	v_writelane_b32 v249, s39, 36
	v_writelane_b32 v249, s40, 37
	v_writelane_b32 v249, s41, 38
	v_writelane_b32 v249, s42, 39
	v_writelane_b32 v249, s43, 40
	v_writelane_b32 v249, s44, 41
	v_writelane_b32 v249, s45, 42
	v_writelane_b32 v249, s46, 43
	v_writelane_b32 v249, s47, 44
	v_writelane_b32 v249, s48, 45
	v_writelane_b32 v249, s49, 46
	v_writelane_b32 v249, s50, 47
	v_writelane_b32 v249, s51, 48
	s_nop 0
	v_readlane_b32 s12, v249, 1
	v_readlane_b32 s26, v249, 15
	v_readlane_b32 s27, v249, 16
	s_add_u32 s0, s26, 0x3580000
	s_addc_u32 s1, s27, 0
	v_readlane_b32 s13, v249, 2
	v_readlane_b32 s14, v249, 3
	v_readlane_b32 s15, v249, 4
	v_readlane_b32 s16, v249, 5
	v_readlane_b32 s17, v249, 6
	v_readlane_b32 s18, v249, 7
	v_readlane_b32 s19, v249, 8
	v_readlane_b32 s20, v249, 9
	v_readlane_b32 s21, v249, 10
	v_readlane_b32 s22, v249, 11
	v_readlane_b32 s23, v249, 12
	v_readlane_b32 s24, v249, 13
	v_readlane_b32 s25, v249, 14
	v_writelane_b32 v249, s0, 49
	s_nop 1
	v_writelane_b32 v249, s1, 50
	s_getreg_b32 s0, hwreg(HW_REG_XCC_ID, 0, 4)
	s_and_b32 s97, s0, 15
	s_mov_b64 s[0:1], exec
	v_writelane_b32 v249, s2, 51
	s_nop 1
	v_writelane_b32 v249, s3, 52
	s_and_b64 s[2:3], s[0:1], s[2:3]
	s_mov_b64 exec, s[2:3]
	s_cbranch_execz .LBB0_17
	s_mov_b64 s[2:3], exec
	v_mbcnt_lo_u32_b32 v0, s2, 0
	v_mbcnt_hi_u32_b32 v0, s3, v0
	v_cmp_eq_u32_e32 vcc, 0, v0
	s_and_b64 s[4:5], exec, vcc
	s_mov_b64 exec, s[4:5]
	s_cbranch_execz .LBB0_17
	s_bcnt1_i32_b64 s2, s[2:3]
	s_lshl_b32 s4, s97, 8
	v_mov_b32_e32 v1, s2
	v_readlane_b32 s2, v249, 49
	v_mov_b32_e32 v0, s4
	v_readlane_b32 s3, v249, 50
	s_nop 4
	s_and_b32 s5, s96, 7
	s_mul_i32 s6, s5, s5
	s_lshl_b32 s6, s6, 16
	s_or_b32 s5, s5, s6
	v_mov_b32_e32 v2, s5
	global_atomic_add v2, v0, v2, s[2:3] offset:1152 sc0
	s_waitcnt vmcnt(0)
	global_atomic_add v0, v1, s[2:3] offset:1024

; __device__ __forceinline__ unsigned xb_ld(unsigned* p)              { return __hip_atomic_load(p, __ATOMIC_RELAXED, __HIP_MEMORY_SCOPE_AGENT); }
; __device__ __forceinline__ void xcd_barrier_complete(unsigned* bar, unsigned x, unsigned& nloc, unsigned& nx) {
;     const unsigned G = gridDim.x * gridDim.y * gridDim.z;
;     unsigned sum, cnt, mine, sp = 0u;
;     for (;;) {
;         sum = 0u; cnt = 0u; mine = 0u;
; #pragma unroll
;         for (unsigned j = 0; j < 16; ++j) { const unsigned c = xb_ld(&bar[XB_XCNT(j)]); sum += c; cnt += (c > 0u) ? 1u : 0u; mine = (j == x) ? c : mine; }
;         if (sum == G) break;
;         __builtin_amdgcn_s_sleep(1);
;         if ((++sp & 255u) == 0u) { if (xb_ld(&bar[XB_TMO])) break; if (sp > XB_SPIN_CAP) { atomicAdd(&bar[XB_TMO], 1u); break; } }
;     }
;     nloc = mine > 0u ? mine : 1u; nx = cnt > 0u ? cnt : 1u;
; }
; __device__ __forceinline__ void xcd_barrier(const XcdBarrier& b) {
;     ...
;         unsigned nloc = b.st[0], nx = b.st[1];
;         if (nloc == 0u) { xcd_barrier_complete(bar, b.x, nloc, nx); b.st[0] = nloc; b.st[1] = nx; }
.LBB0_274:
	s_mov_b64 s[90:91], exec
	s_add_u32 s6, s4, 0x200
	s_addc_u32 s7, s5, 0
	s_mov_b64 exec, 0xffff
	v_mbcnt_lo_u32_b32 v16, -1, 0
	v_lshlrev_b32_e32 v16, 8, v16
	global_load_dword v17, v16, s[6:7] sc1
	s_waitcnt vmcnt(0)
	v_cmp_eq_u32_e32 vcc, 32, v17
	v_cmp_eq_u32_e64 s[36:37], 0, v17
	s_or_b64 s[36:37], s[36:37], vcc
	global_load_dword v17, v16, s[6:7] offset:128 sc1
	s_waitcnt vmcnt(0)
	v_lshrrev_b32_e32 v16, 16, v17
	v_and_b32_e32 v17, 0xffff, v17
	v_mul_lo_u32 v17, v17, v17
	v_lshlrev_b32_e32 v16, 5, v16
	v_cmp_eq_u32_e32 vcc, v16, v17
	s_and_b64 s[36:37], s[36:37], vcc
	s_mov_b64 exec, s[90:91]
	s_cmp_eq_u64 s[36:37], 0xffff
	s_cselect_b32 s98, 1, 0
	s_and_b32 s98, s98, s12
	s_cmp_eq_u32 s97, 0
	s_cselect_b64 vcc, -1, 0
	s_cmp_eq_u32 s97, 1
	v_cndmask_b32_e32 v16, 0, v15, vcc
	s_cselect_b64 vcc, -1, 0
	s_cmp_eq_u32 s97, 2
	v_cndmask_b32_e32 v16, v16, v0, vcc
	s_cselect_b64 vcc, -1, 0
	s_cmp_eq_u32 s97, 3
	v_cndmask_b32_e32 v16, v16, v1, vcc
	s_cselect_b64 vcc, -1, 0
	s_cmp_eq_u32 s97, 4
	v_cndmask_b32_e32 v16, v16, v2, vcc
	s_cselect_b64 vcc, -1, 0
	s_cmp_eq_u32 s97, 5
	v_cndmask_b32_e32 v16, v16, v3, vcc
	s_cselect_b64 vcc, -1, 0
	s_cmp_eq_u32 s97, 6
	v_cndmask_b32_e32 v16, v16, v4, vcc
	s_cselect_b64 vcc, -1, 0
	s_cmp_eq_u32 s97, 7
	v_cndmask_b32_e32 v16, v16, v5, vcc
	s_cselect_b64 vcc, -1, 0
	s_cmp_eq_u32 s97, 8
	v_cndmask_b32_e32 v16, v16, v6, vcc
	s_cselect_b64 vcc, -1, 0
	s_cmp_eq_u32 s97, 9
	v_cndmask_b32_e32 v16, v16, v7, vcc
	s_cselect_b64 vcc, -1, 0
	s_cmp_eq_u32 s97, 10
	v_cndmask_b32_e32 v16, v16, v8, vcc
	s_cselect_b64 vcc, -1, 0
	s_cmp_eq_u32 s97, 11
	v_cndmask_b32_e32 v16, v16, v9, vcc
	s_cselect_b64 vcc, -1, 0
	s_cmp_eq_u32 s97, 12
	v_cndmask_b32_e32 v16, v16, v10, vcc
	s_cselect_b64 vcc, -1, 0
	s_cmp_eq_u32 s97, 13
	v_cndmask_b32_e32 v16, v16, v11, vcc
	s_cselect_b64 vcc, -1, 0
	s_cmp_eq_u32 s97, 14
	v_cndmask_b32_e32 v16, v16, v12, vcc
	s_cselect_b64 vcc, -1, 0
	s_cmp_eq_u32 s97, 15
	v_cndmask_b32_e32 v16, v16, v13, vcc
	s_cselect_b64 vcc, -1, 0
	v_cndmask_b32_e32 v16, v16, v14, vcc
	v_cmp_ne_u32_e32 vcc, 0, v15
	s_add_i32 s4, 0, 0x20400
	s_nop 0
	v_cndmask_b32_e64 v15, 0, 1, vcc
	v_cmp_ne_u32_e32 vcc, 0, v0
	s_nop 1
	v_addc_co_u32_e32 v0, vcc, 0, v15, vcc
	v_cmp_ne_u32_e32 vcc, 0, v1
	s_nop 1
	v_cndmask_b32_e64 v1, 0, 1, vcc
	v_cmp_ne_u32_e32 vcc, 0, v2
	v_max_u32_e32 v2, 1, v16
	s_nop 0
	v_addc_co_u32_e32 v0, vcc, v0, v1, vcc
	v_cmp_ne_u32_e32 vcc, 0, v3
	s_nop 1
	v_cndmask_b32_e64 v1, 0, 1, vcc
	v_cmp_ne_u32_e32 vcc, 0, v4
	s_nop 1
	v_addc_co_u32_e32 v0, vcc, v0, v1, vcc
	v_cmp_ne_u32_e32 vcc, 0, v5
	s_nop 1
	v_cndmask_b32_e64 v1, 0, 1, vcc
	v_cmp_ne_u32_e32 vcc, 0, v6
	s_nop 1
	v_addc_co_u32_e32 v0, vcc, v0, v1, vcc
	v_cmp_ne_u32_e32 vcc, 0, v7
	s_nop 1
	v_cndmask_b32_e64 v1, 0, 1, vcc
	v_cmp_ne_u32_e32 vcc, 0, v8
	s_nop 1
	v_addc_co_u32_e32 v0, vcc, v0, v1, vcc
	v_cmp_ne_u32_e32 vcc, 0, v9
	s_nop 1
	v_cndmask_b32_e64 v1, 0, 1, vcc
	v_cmp_ne_u32_e32 vcc, 0, v10
	s_nop 1
	v_addc_co_u32_e32 v0, vcc, v0, v1, vcc
	v_cmp_ne_u32_e32 vcc, 0, v11
	s_nop 1
	v_cndmask_b32_e64 v1, 0, 1, vcc
	v_cmp_ne_u32_e32 vcc, 0, v12
	s_nop 1
	v_addc_co_u32_e32 v0, vcc, v0, v1, vcc
	v_cmp_ne_u32_e32 vcc, 0, v13
	s_nop 1
	v_cndmask_b32_e64 v1, 0, 1, vcc
	v_cmp_ne_u32_e32 vcc, 0, v14
	s_nop 1
	v_addc_co_u32_e32 v0, vcc, v0, v1, vcc
	v_mov_b32_e32 v1, s4
	s_add_i32 s4, 0, 0x20404
	v_max_u32_e32 v0, 1, v0
	ds_write_b32 v1, v2
	v_mov_b32_e32 v1, s4
	ds_write_b32 v1, v0

; __device__ __forceinline__ unsigned xb_ld(unsigned* p)              { return __hip_atomic_load(p, __ATOMIC_RELAXED, __HIP_MEMORY_SCOPE_AGENT); }
; __device__ __forceinline__ unsigned xb_add(unsigned* p, unsigned v) { return __hip_atomic_fetch_add(p, v, __ATOMIC_RELAXED, __HIP_MEMORY_SCOPE_AGENT); }
; #define XB_SPIN(cond, bar) do { unsigned _sp = 0; while (cond) { __builtin_amdgcn_s_sleep(1); \
;     if ((++_sp & 255u) == 0u) { if (xb_ld(&(bar)[XB_TMO])) break; if (_sp > XB_SPIN_CAP) { atomicAdd(&(bar)[XB_TMO], 1u); break; } } } } while (0)
; __device__ __forceinline__ void xcd_barrier(const XcdBarrier& b) {
;     ...
;         const unsigned old = xb_add(&bar[XB_XSUB(b.x)], 1u);
;         const unsigned gen = old / nloc;
;         if (old + 1u == (gen + 1u) * nloc) {
;             __builtin_amdgcn_fence(__ATOMIC_RELEASE, "agent");
;             asm volatile("s_waitcnt vmcnt(0)" ::: "memory");
;             const unsigned og = xb_add(&bar[XB_TOP], 1u);
;             const unsigned tg = og / nx;
;             if (og + 1u == (tg + 1u) * nx) xb_add(&bar[XB_TOPGEN], 1u);
;             else XB_SPIN(xb_ld(&bar[XB_TOPGEN]) == tg, bar);
.LBB0_1863:
	s_andn2_saveexec_b64 s[6:7], s[6:7]
	s_cbranch_execz .LBB0_1883
	s_mov_b64 s[6:7], exec
	s_waitcnt lgkmcnt(0)
	s_cmp_lg_u32 s98, 0
	s_cbranch_scc1 .LBB0_1880
	buffer_wbl2 sc1
	s_waitcnt lgkmcnt(0)
	s_waitcnt vmcnt(0)
	v_mbcnt_lo_u32_b32 v1, s6, 0
	v_mbcnt_hi_u32_b32 v1, s7, v1
	v_cmp_eq_u32_e32 vcc, 0, v1
	s_and_saveexec_b64 s[8:9], vcc
	s_cbranch_execz .LBB0_1866
	s_bcnt1_i32_b64 s6, s[6:7]
	v_mov_b32_e32 v2, 0x3583000
	v_mov_b32_e32 v3, s6
	global_atomic_add v2, v2, v3, s[30:31] offset:1024 sc0

; __global__ void __launch_bounds__(512, 2) fwd_mega(Args args) {
	.amdhsa_kernel _Z8fwd_mega4Args
		.amdhsa_group_segment_fixed_size 0
		.amdhsa_private_segment_fixed_size 0
		.amdhsa_kernarg_size 520
		.amdhsa_user_sgpr_count 2
		.amdhsa_user_sgpr_dispatch_ptr 0
		.amdhsa_user_sgpr_queue_ptr 0
		.amdhsa_user_sgpr_kernarg_segment_ptr 1
		.amdhsa_user_sgpr_dispatch_id 0
		.amdhsa_user_sgpr_kernarg_preload_length 0
		.amdhsa_user_sgpr_kernarg_preload_offset 0
		.amdhsa_user_sgpr_private_segment_size 0
		.amdhsa_uses_dynamic_stack 0
		.amdhsa_enable_private_segment 0
		.amdhsa_system_sgpr_workgroup_id_x 1
		.amdhsa_system_sgpr_workgroup_id_y 0
		.amdhsa_system_sgpr_workgroup_id_z 0
		.amdhsa_system_sgpr_workgroup_info 0
		.amdhsa_system_vgpr_workitem_id 2
		.amdhsa_next_free_vgpr 256
		.amdhsa_next_free_sgpr 99
		.amdhsa_accum_offset 256
		.amdhsa_reserve_vcc 1
		.amdhsa_float_round_mode_32 0
		.amdhsa_float_round_mode_16_64 0
		.amdhsa_float_denorm_mode_32 3
		.amdhsa_float_denorm_mode_16_64 3
		.amdhsa_dx10_clamp 1
		.amdhsa_ieee_mode 1
		.amdhsa_fp16_overflow 0
		.amdhsa_tg_split 0
		.amdhsa_exception_fp_ieee_invalid_op 0
		.amdhsa_exception_fp_denorm_src 0
		.amdhsa_exception_fp_ieee_div_zero 0
		.amdhsa_exception_fp_ieee_overflow 0
		.amdhsa_exception_fp_ieee_underflow 0
		.amdhsa_exception_fp_ieee_inexact 0
		.amdhsa_exception_int_div_zero 0
	.end_amdhsa_kernel

; __global__ void __launch_bounds__(512, 2) fwd_mega(Args args) {
amdhsa.kernels:
  - .agpr_count:     0
    .args:
      - .offset:         0
        .size:           264
        .value_kind:     by_value
      - .offset:         264
        .size:           4
        .value_kind:     hidden_block_count_x
      - .offset:         268
        .size:           4
        .value_kind:     hidden_block_count_y
      - .offset:         272
        .size:           4
        .value_kind:     hidden_block_count_z
      - .offset:         276
        .size:           2
        .value_kind:     hidden_group_size_x
      - .offset:         278
        .size:           2
        .value_kind:     hidden_group_size_y
      - .offset:         280
        .size:           2
        .value_kind:     hidden_group_size_z
      - .offset:         282
        .size:           2
        .value_kind:     hidden_remainder_x
      - .offset:         284
        .size:           2
        .value_kind:     hidden_remainder_y
      - .offset:         286
        .size:           2
        .value_kind:     hidden_remainder_z
      - .offset:         304
        .size:           8
        .value_kind:     hidden_global_offset_x
      - .offset:         312
        .size:           8
        .value_kind:     hidden_global_offset_y
      - .offset:         320
        .size:           8
        .value_kind:     hidden_global_offset_z
      - .offset:         328
        .size:           2
        .value_kind:     hidden_grid_dims
      - .offset:         352
        .size:           8
        .value_kind:     hidden_multigrid_sync_arg
      - .offset:         384
        .size:           4
        .value_kind:     hidden_dynamic_lds_size
    .group_segment_fixed_size: 0
    .kernarg_segment_align: 8
    .kernarg_segment_size: 520
    .language:       OpenCL C
    .language_version:
      - 2
      - 0
    .max_flat_workgroup_size: 512
    .name:           _Z8fwd_mega4Args
    .private_segment_fixed_size: 0
    .sgpr_count:     105
    .sgpr_spill_count: 88
    .symbol:         _Z8fwd_mega4Args.kd
    .uniform_work_group_size: 1
    .uses_dynamic_stack: false
    .vgpr_count:     256
    .vgpr_spill_count: 0
    .wavefront_size: 64
